# v34 with the whole instruction stream shifted by 4 bytes (one s_nop at kernel entry): code placement check
# speedup vs baseline: 1.0000x; 1.0000x over previous
_Z10fwd_kernel4Args:
	s_mov_b64 s[58:59], s[0:1]
	s_nop 0
	s_load_dword s0, s[0:1], 0x130
	s_add_u32 s4, s58, 0x130
	s_addc_u32 s5, s59, 0
	v_readfirstlane_b32 s6, v0
	v_writelane_b32 v252, s4, 0
	s_nop 1
	v_writelane_b32 v252, s5, 1
	s_waitcnt lgkmcnt(0)
	v_writelane_b32 v252, s0, 2
	s_and_b32 s0, s0, 7
	v_writelane_b32 v252, s2, 3
	s_cmp_lg_u32 s0, 0
	v_writelane_b32 v252, s2, 4
	s_cbranch_scc1 .LBB0_2
	s_load_dword s0, s[58:59], 0x130
	v_readlane_b32 s3, v252, 3
	s_ashr_i32 s1, s3, 31
	s_lshr_b32 s1, s1, 29
	s_add_i32 s1, s3, s1
	s_ashr_i32 s2, s1, 3
	s_and_b32 s1, s1, -8
	s_waitcnt lgkmcnt(0)
	s_ashr_i32 s0, s0, 3
	s_sub_i32 s1, s3, s1
	s_mul_i32 s0, s0, s1
	s_add_i32 s0, s0, s2
	v_writelane_b32 v252, s0, 4
